# P3: V tile global loads hoisted to loop top and K LDS writes moved to loop end (full-iteration latency cover)
# speedup vs baseline: 1.1338x; 1.0069x over previous
; template <int MODE>
; __device__ void attn_item(const Params& p, char* lds, int grp  , int b, int h, int qblk, int dry) {
;     ...
;   auto gloadK = [&](int kt) {
;     const bf16_t* ktile = kg + (size_t)kt * 64 * LDH;
; #pragma unroll
;     for (int i = 0; i < NKC; ++i) {
;       if (MODE == 0) rk[i] = *(const u32x4*)(ktile + koff[i]);
;       else {
;         const int q = tid + 256 * i; const int row = q / KCH, ch = q % KCH;
;         const bf16_t* src = (ch < 8) ? kg + (size_t)(kt * 64 + row) * LDH + ch * 8 : kpe + (size_t)(kt * 64 + row) * 32 + (ch - 8) * 8;
;         rk[i] = *(const u32x4*)src;
;       }
;     }
;   };
;   auto gloadV = [&](int kt) {
;     const bf16_t* vtile = vg + kt * 64;
; #pragma unroll
;     for (int i = 0; i < NVC; ++i) rv[i] = *(const u32x4*)(vtile + voff[i]);
;   };
;     ...
;   for (int kt = 0; kt < nkt; ++kt) {
;     const bool more = (kt + 1 < nkt);
;     if (more) { gloadK(kt + 1); if (MODE == 1) gloadV(kt + 1); }
.LBB0_448:
	s_add_i32 s3, s27, 1
	s_cmp_lt_u32 s3, s26
	s_cselect_b64 s[0:1], -1, 0
	s_cmp_ge_u32 s3, s26
	s_cbranch_scc1 .LBB0_450
	v_lshl_add_u64 v[64:65], s[50:51], 0, v[152:153]
	v_lshl_add_u64 v[66:67], s[50:51], 0, v[154:155]
	global_load_dwordx4 v[112:115], v[64:65], off
	global_load_dwordx4 v[116:119], v[66:67], off
	v_lshl_add_u64 v[64:65], s[50:51], 0, v[156:157]
	v_lshl_add_u64 v[66:67], s[50:51], 0, v[158:159]
	global_load_dwordx4 v[120:123], v[64:65], off
	global_load_dwordx4 v[124:127], v[66:67], off
	s_lshl_b64 s[44:45], s[24:25], 1
	s_add_u32 s44, s48, s44
	s_addc_u32 s45, s49, s45
	global_load_dwordx4 v[128:131], v212, s[44:45]
	global_load_dwordx4 v[132:135], v213, s[44:45]
	global_load_dwordx4 v[136:139], v214, s[44:45]
	global_load_dwordx4 v[140:143], v215, s[44:45]

; __device__ __forceinline__ unsigned pk2(float lo, float hi) { f32v2_t v = {lo, hi}; bf16v2_t r = __builtin_convertvector(v, bf16v2_t); return __builtin_bit_cast(unsigned, r); }
; __device__ __forceinline__ f32x16 mfma32(bf16x8 a, bf16x8 b, f32x16 c) { return __builtin_amdgcn_mfma_f32_32x32x16_bf16(a, b, c, 0, 0, 0); }
; template <int MODE>
; __device__ void attn_item(const Params& p, char* lds, int grp  , int b, int h, int qblk, int dry) {
;     ...
;       if (MODE == 0 && more) { lwriteK((kt + 1) & 1); gloadV(kt + 1); }
;       f32v2_t ps2 = {0.f, 0.f}; const f32v2_t m2 = {m, m};
;       const char* vp0 = base + KBYTES + l31 * 144 + hh * 16;
; #pragma unroll
;       for (int sub = 0; sub < 2; ++sub) {
; #pragma unroll
;         for (int r = 0; r < 16; r += 2) {
;           f32v2_t v = (f32v2_t){S[sub][r], S[sub][r + 1]} - m2;
;           v[0] = __builtin_amdgcn_exp2f(v[0]); v[1] = __builtin_amdgcn_exp2f(v[1]);
;           S[sub][r] = v[0]; S[sub][r + 1] = v[1]; ps2 += v;
;         }
; #pragma unroll
;         for (int s = 0; s < 2; ++s) {
;           u32x4 w;
;           w.x = pk2(S[sub][8 * s + 0], S[sub][8 * s + 1]); w.y = pk2(S[sub][8 * s + 2], S[sub][8 * s + 3]);
;           w.z = pk2(S[sub][8 * s + 4], S[sub][8 * s + 5]); w.w = pk2(S[sub][8 * s + 6], S[sub][8 * s + 7]);
;           const bf16x8 pf = __builtin_bit_cast(bf16x8, w);
; #pragma unroll
;           for (int blk = 0; blk < DV / 32; ++blk) {
;             bf16x8 vf = *(const bf16x8*)(vp0 + blk * 32 * 144 + sub * 64 + s * 32);
;             O[blk] = mfma32(vf, pf, O[blk]);
;           }
;         }
;       }
;       l += ps2[0] + ps2[1];
;     }
;     if (more) { if (MODE == 1) lwriteK((kt + 1) & 1); lwriteV((kt + 1) & 1); }
;     __syncthreads();
.LBB0_456:
	v_sub_f32_e32 v80, v80, v168
	v_sub_f32_e32 v81, v81, v168
	v_sub_f32_e32 v82, v82, v168
	v_sub_f32_e32 v83, v83, v168
	v_sub_f32_e32 v84, v84, v168
	v_sub_f32_e32 v85, v85, v168
	v_sub_f32_e32 v86, v86, v168
	v_sub_f32_e32 v87, v87, v168
	v_add3_u32 v216, s27, v195, v182
	v_exp_f32_e32 v80, v80
	v_exp_f32_e32 v81, v81
	v_exp_f32_e32 v82, v82
	v_exp_f32_e32 v83, v83
	v_exp_f32_e32 v84, v84
	v_exp_f32_e32 v85, v85
	v_exp_f32_e32 v86, v86
	v_exp_f32_e32 v87, v87
	ds_read_b128 v[238:241], v216 offset:17408
	ds_read_b128 v[242:245], v216 offset:17440
	v_cvt_pk_bf16_f32 v234, v80, v81
	v_cvt_pk_bf16_f32 v235, v82, v83
	v_cvt_pk_bf16_f32 v236, v84, v85
	v_cvt_pk_bf16_f32 v237, v86, v87
	v_sub_f32_e32 v88, v88, v168
	v_sub_f32_e32 v89, v89, v168
	v_sub_f32_e32 v90, v90, v168
	v_sub_f32_e32 v91, v91, v168
	s_waitcnt lgkmcnt(1)
	v_mfma_f32_32x32x16_bf16 v[32:47], v[238:241], v[234:237], v[32:47]
	ds_read_b128 v[238:241], v216 offset:22016
	v_add_f32_e64 v92, v92, -v168
	v_add_f32_e64 v93, v93, -v168
	v_add_f32_e64 v94, v94, -v168
	v_add_f32_e64 v95, v95, -v168
	v_exp_f32_e32 v88, v88
	v_exp_f32_e32 v89, v89
	v_exp_f32_e32 v90, v90
	v_exp_f32_e32 v91, v91
	s_waitcnt lgkmcnt(0)
	v_mfma_f32_32x32x16_bf16 v[48:63], v[238:241], v[234:237], v[48:63]
	ds_read_b128 v[238:241], v216 offset:26624
	v_exp_f32_e32 v92, v92
	v_exp_f32_e32 v93, v93
	v_exp_f32_e32 v94, v94
	v_exp_f32_e32 v95, v95
	v_sub_f32_e32 v64, v64, v168
	v_sub_f32_e32 v65, v65, v168
	v_sub_f32_e32 v66, v66, v168
	v_sub_f32_e32 v67, v67, v168
	s_waitcnt lgkmcnt(0)
	v_mfma_f32_32x32x16_bf16 v[0:15], v[238:241], v[234:237], v[0:15]
	ds_read_b128 v[238:241], v216 offset:31232
	v_add_f32_e64 v68, v68, -v168
	v_add_f32_e64 v69, v69, -v168
	v_add_f32_e64 v70, v70, -v168
	v_add_f32_e64 v71, v71, -v168
	v_exp_f32_e32 v64, v64
	v_exp_f32_e32 v65, v65
	v_exp_f32_e32 v66, v66
	v_exp_f32_e32 v67, v67
	s_waitcnt lgkmcnt(0)
	v_mfma_f32_32x32x16_bf16 v[16:31], v[238:241], v[234:237], v[16:31]
	ds_read_b128 v[238:241], v216 offset:22048
	v_cvt_pk_bf16_f32 v234, v88, v89
	v_cvt_pk_bf16_f32 v235, v90, v91
	v_cvt_pk_bf16_f32 v236, v92, v93
	v_cvt_pk_bf16_f32 v237, v94, v95
	v_exp_f32_e32 v68, v68
	v_exp_f32_e32 v69, v69
	s_waitcnt lgkmcnt(0)
	v_mfma_f32_32x32x16_bf16 v[48:63], v[238:241], v[234:237], v[48:63]
	ds_read_b128 v[238:241], v216 offset:26656
	v_exp_f32_e32 v70, v70
	v_exp_f32_e32 v71, v71
	v_sub_f32_e32 v72, v72, v168
	v_sub_f32_e32 v73, v73, v168
	v_sub_f32_e32 v74, v74, v168
	v_sub_f32_e32 v75, v75, v168
	v_sub_f32_e32 v76, v76, v168
	v_sub_f32_e32 v77, v77, v168
	v_sub_f32_e32 v78, v78, v168
	v_sub_f32_e32 v79, v79, v168
	s_waitcnt lgkmcnt(0)
	v_mfma_f32_32x32x16_bf16 v[0:15], v[238:241], v[234:237], v[0:15]
	ds_read_b128 v[238:241], v216 offset:31264
	v_exp_f32_e32 v72, v72
	v_exp_f32_e32 v73, v73
	v_exp_f32_e32 v74, v74
	v_exp_f32_e32 v75, v75
	v_exp_f32_e32 v76, v76
	v_exp_f32_e32 v77, v77
	s_waitcnt lgkmcnt(0)
	v_mfma_f32_32x32x16_bf16 v[16:31], v[238:241], v[234:237], v[16:31]
	ds_read_b128 v[238:241], v216 offset:17472
	v_exp_f32_e32 v78, v78
	v_exp_f32_e32 v79, v79
	s_and_b64 vcc, exec, s[44:45]
	v_mfma_f32_32x32x16_bf16 v[32:47], v[242:245], v[234:237], v[32:47]
	ds_read_b128 v[242:245], v216 offset:22080
	v_cvt_pk_bf16_f32 v234, v64, v65
	v_cvt_pk_bf16_f32 v235, v66, v67
	v_cvt_pk_bf16_f32 v236, v68, v69
	v_cvt_pk_bf16_f32 v237, v70, v71
	s_waitcnt lgkmcnt(1)
	s_nop 0
	v_mfma_f32_32x32x16_bf16 v[32:47], v[238:241], v[234:237], v[32:47]
	ds_read_b128 v[238:241], v216 offset:26688
	s_waitcnt lgkmcnt(1)
	v_mfma_f32_32x32x16_bf16 v[48:63], v[242:245], v[234:237], v[48:63]
	ds_read_b128 v[242:245], v216 offset:31296
	s_waitcnt lgkmcnt(1)
	v_mfma_f32_32x32x16_bf16 v[0:15], v[238:241], v[234:237], v[0:15]
	ds_read_b128 v[238:241], v216 offset:17504
	s_waitcnt lgkmcnt(1)
	v_mfma_f32_32x32x16_bf16 v[16:31], v[242:245], v[234:237], v[16:31]
	ds_read_b128 v[242:245], v216 offset:22112
	v_cvt_pk_bf16_f32 v234, v72, v73
	v_cvt_pk_bf16_f32 v235, v74, v75
	v_cvt_pk_bf16_f32 v236, v76, v77
	v_cvt_pk_bf16_f32 v237, v78, v79
	s_waitcnt lgkmcnt(1)
	s_nop 0
	v_mfma_f32_32x32x16_bf16 v[32:47], v[238:241], v[234:237], v[32:47]
	ds_read_b128 v[238:241], v216 offset:26720
	s_waitcnt lgkmcnt(1)
	v_mfma_f32_32x32x16_bf16 v[48:63], v[242:245], v[234:237], v[48:63]
	ds_read_b128 v[216:219], v216 offset:31328
	s_waitcnt lgkmcnt(1)
	v_mfma_f32_32x32x16_bf16 v[0:15], v[238:241], v[234:237], v[0:15]
	s_waitcnt lgkmcnt(0)
	v_mfma_f32_32x32x16_bf16 v[16:31], v[216:219], v[234:237], v[16:31]
	s_cbranch_vccnz .LBB0_458
	s_bitcmp1_b32 s3, 0
	s_cselect_b32 s0, 0x8c00, 0
	v_add3_u32 v217, s0, v174, v175
	s_waitcnt vmcnt(7)
	ds_write_b128 v217, v[112:115]
	v_add3_u32 v217, s0, v176, v175
	s_waitcnt vmcnt(6)
	ds_write_b128 v217, v[116:119]
	v_add3_u32 v217, s0, v177, v175
	s_waitcnt vmcnt(5)
	ds_write_b128 v217, v[120:123]
	v_add3_u32 v217, s0, v178, v175
	s_waitcnt vmcnt(4)
	ds_write_b128 v217, v[124:127]
	v_add3_u32 v216, s0, v179, v187
	v_add3_u32 v217, s0, v190, v187
	v_add3_u32 v218, s0, v191, v187
	v_add3_u32 v219, s0, v192, v187
	s_waitcnt vmcnt(3)
	ds_write_b128 v216, v[128:131] offset:17408
	s_waitcnt vmcnt(2)
	ds_write_b128 v217, v[132:135] offset:17408
	s_waitcnt vmcnt(1)
	ds_write_b128 v218, v[136:139] offset:17408
	s_waitcnt vmcnt(0)
	ds_write_b128 v219, v[140:143] offset:17408
